# placement: F3 loop head at 0 mod 64 (F1G 56, FFN-F2 40)
# speedup vs baseline: 1.0075x; 1.0002x over previous
.LBB0_1154:
	s_lshl_b32 s6, s20, 1
	s_or_b32 s13, s6, 1
	s_mul_i32 s7, s13, 0x3000
	s_mul_hi_u32 s6, s13, 0x3000
	s_add_u32 s7, s18, s7
	s_addc_u32 s6, s19, s6
	s_add_u32 s42, s7, 0x20000
	s_addc_u32 s43, s6, 0
	s_lshl_b32 s72, s20, 11
	s_lshl_b64 s[6:7], s[72:73], 2
	s_waitcnt lgkmcnt(0)
	s_add_u32 s36, s4, s6
	s_addc_u32 s37, s5, s7
	s_add_u32 s14, s18, 0x40000
	s_mul_i32 s4, s20, 0xc000
	s_addc_u32 s15, s19, 0
	s_add_i32 s6, s4, 0xc000
	s_and_b64 s[4:5], exec, s[8:9]
	s_cselect_b32 s72, 0, s6
	s_lshl_b64 s[4:5], s[72:73], 2
	s_add_u32 s6, s14, s4
	s_addc_u32 s7, s15, s5
	s_mul_hi_u32 s4, s13, 0x18000
	s_mul_i32 s13, s13, 0x18000
	s_add_u32 s40, s14, s13
	s_addc_u32 s41, s15, s4
	s_add_u32 s46, s18, 0x100000
	s_addc_u32 s47, s19, 0
	s_add_u32 s48, s18, 0x10200
	s_addc_u32 s49, s19, 0
	s_and_b32 s8, s3, 3
	s_lshl_b32 s3, s12, 6
	s_lshl_b32 s9, s12, 13
	s_lshl_b32 s13, s8, 12
	s_add_u32 s18, s18, 0x8800000
	s_addc_u32 s19, s19, 0
	s_add_i32 m0, s28, 0x18000
	v_lshl_add_u64 v[6:7], v[6:7], 0, s[74:75]
	s_waitcnt vmcnt(2)
	s_barrier
	global_load_lds_dwordx4 v[6:7], off
	v_lshl_add_u64 v[4:5], v[4:5], 0, s[74:75]
	s_add_i32 m0, s28, 0x1a000
	s_add_i32 s44, s28, 0x8000
	s_add_i32 s45, s28, 0xa000
	global_load_lds_dwordx4 v[4:5], off
	v_lshl_add_u64 v[0:1], v[0:1], 0, s[74:75]
	s_mov_b32 m0, s44
	s_add_u32 s4, s30, 0x160080
	global_load_lds_dwordx4 v[0:1], off
	v_lshl_add_u64 v[0:1], v[2:3], 0, s[74:75]
	s_mov_b32 m0, s45
	s_addc_u32 s5, s31, 0
	global_load_lds_dwordx4 v[0:1], off
	s_add_i32 m0, s28, 0x1c000
	v_lshl_add_u64 v[0:1], s[4:5], 0, v[176:177]
	global_load_lds_dwordx4 v[0:1], off
	v_lshl_add_u64 v[0:1], s[4:5], 0, v[182:183]
	s_add_i32 m0, s28, 0x1e000
	v_lshlrev_b32_e32 v5, 2, v15
	global_load_lds_dwordx4 v[0:1], off
	v_and_b32_e32 v0, 15, v15
	v_bfe_u32 v1, v15, 4, 2
	v_or_b32_e32 v184, s3, v0
	v_lshlrev_b32_e32 v2, 4, v1
	v_lshlrev_b32_e32 v3, 2, v184
	s_cmpk_lt_u32 s2, 0x100
	v_lshl_or_b32 v2, v0, 6, v2
	v_and_b32_e32 v4, 32, v3
	v_and_b32_e32 v5, 32, v5
	s_cselect_b64 s[52:53], -1, 0
	s_add_i32 s2, s3, 0x80
	v_bitop3_b32 v4, v2, s9, v4 bitop3:0xde
	v_bitop3_b32 v204, v2, s13, v5 bitop3:0xde
	v_lshlrev_b32_e32 v2, 4, v0
	v_ashrrev_i32_e32 v185, 31, v184
	v_or_b32_e32 v0, s2, v0
	s_ashr_i32 s2, s3, 31
	v_lshl_add_u64 v[186:187], v[184:185], 2, s[6:7]
	v_mov_b32_e32 v185, s2
	v_lshl_add_u64 v[188:189], v[184:185], 2, s[6:7]
	s_mov_b64 s[2:3], 0xc0
	v_lshl_add_u64 v[194:195], v[188:189], 0, s[2:3]
	s_lshl_b32 s2, s8, 2
	s_lshl_b32 s9, s12, 10
	s_add_i32 s2, s2, 0
	s_add_i32 s2, s2, s9
	s_add_i32 s6, s2, 0x20c00
	v_readlane_b32 s2, v254, 57
	s_movk_i32 s7, 0x1600
	v_lshlrev_b32_e32 v6, 3, v1
	v_cmp_eq_u32_e64 s[4:5], 0, v1
	v_lshl_add_u32 v209, v0, 2, s2
	v_lshrrev_b32_e32 v1, 1, v8
	v_mul_lo_u32 v0, v9, s7
	v_add_u32_e32 v185, s2, v3
	v_mad_u64_u32 v[0:1], s[2:3], v1, s97, v[0:1]
	v_or_b32_e32 v0, v0, v10
	v_lshl_or_b32 v205, s8, 5, v6
	v_add_lshl_u32 v0, v0, v11, 1
	v_mov_b32_e32 v1, v177
	s_mov_b64 s[8:9], 0x160080
	v_lshl_add_u64 v[196:197], v[0:1], 0, s[8:9]
	v_lshrrev_b32_e32 v1, 1, v12
	v_mul_lo_u32 v0, v13, s7
	v_mad_u64_u32 v[0:1], s[2:3], v1, s97, v[0:1]
	s_waitcnt vmcnt(6)
	s_cmp_eq_u64 s[16:17], 0
	v_or_b32_e32 v0, v0, v14
	s_cselect_b64 s[54:55], -1, 0
	s_cmp_lg_u64 s[16:17], 0
	v_add_lshl_u32 v0, v0, v16, 1
	v_mov_b32_e32 v1, v177
	s_mov_b32 s58, 0
	v_lshl_add_u64 v[190:191], v[188:189], 0, 64
	v_lshl_add_u64 v[192:193], v[188:189], 0, s[74:75]
	s_cselect_b64 s[56:57], -1, 0
	v_add_u32_e32 v206, 64, v185
	v_add_u32_e32 v207, 0x80, v185
	v_add_u32_e32 v208, 0xc0, v185
	v_add_u32_e32 v220, 64, v209
	v_add_u32_e32 v221, 0x80, v209
	v_add_u32_e32 v222, 0xc0, v209
	v_lshl_add_u64 v[198:199], v[0:1], 0, s[8:9]
	v_add_u32_e32 v223, 0, v4
	v_add_u32_e32 v224, s6, v2
	s_mov_b32 s60, s94
	s_mov_b32 s62, s90
	s_mov_b64 s[68:69], s[0:1]
	s_barrier
	s_branch .LBB0_1157
	s_nop 0
	s_nop 0
